# FFN-in epilogue: the eight rstd table reads issued together at the epilogue head
# speedup vs baseline: 1.0010x; 1.0010x over previous
.LBB0_353:
	ds_read_b32 v220, v149
	ds_read_b32 v221, v149 offset:64
	ds_read_b32 v222, v149 offset:128
	ds_read_b32 v223, v149 offset:192
	ds_read_b32 v224, v150
	ds_read_b32 v225, v149 offset:576
	ds_read_b32 v226, v149 offset:640
	ds_read_b32 v227, v149 offset:704
	v_pk_mul_f32 v[126:127], v[130:131], v[126:127]
	v_pk_mul_f32 v[124:125], v[128:129], v[124:125]
	v_pk_mul_f32 v[118:119], v[122:123], v[118:119]
	v_pk_mul_f32 v[116:117], v[120:121], v[116:117]
	s_waitcnt lgkmcnt(0)
	v_mov_b32_e32 v153, v220
	v_mul_f32_e32 v156, 0xbfb8aa3b, v153
	v_pk_mul_f32 v[158:159], v[130:131], v[156:157] op_sel_hi:[1,0]
	v_pk_mul_f32 v[160:161], v[128:129], v[156:157] op_sel_hi:[1,0]
	v_pk_mul_f32 v[128:129], v[122:123], v[156:157] op_sel_hi:[1,0]
	v_pk_mul_f32 v[130:131], v[120:121], v[156:157] op_sel_hi:[1,0]
	v_exp_f32_e32 v160, v160
	v_exp_f32_e32 v161, v161
	v_exp_f32_e32 v130, v130
	v_exp_f32_e32 v128, v128
	v_exp_f32_e32 v129, v129
	v_exp_f32_e32 v131, v131
	v_exp_f32_e32 v158, v158
	v_exp_f32_e32 v159, v159
	v_pk_add_f32 v[160:161], v[160:161], 1.0 op_sel_hi:[1,0]
	v_pk_add_f32 v[128:129], v[128:129], 1.0 op_sel_hi:[1,0]
	v_pk_add_f32 v[130:131], v[130:131], 1.0 op_sel_hi:[1,0]
	v_pk_add_f32 v[158:159], v[158:159], 1.0 op_sel_hi:[1,0]
	v_rcp_f32_e32 v160, v160
	v_rcp_f32_e32 v161, v161
	v_rcp_f32_e32 v130, v130
	v_rcp_f32_e32 v131, v131
	v_rcp_f32_e32 v128, v128
	v_rcp_f32_e32 v129, v129
	v_rcp_f32_e32 v158, v158
	v_rcp_f32_e32 v159, v159
	v_mul_f32_e32 v162, v153, v153
	v_pk_mul_f32 v[124:125], v[124:125], v[162:163] op_sel_hi:[1,0]
	v_pk_mul_f32 v[116:117], v[116:117], v[162:163] op_sel_hi:[1,0]
	v_pk_mul_f32 v[118:119], v[118:119], v[162:163] op_sel_hi:[1,0]
	v_pk_mul_f32 v[126:127], v[126:127], v[162:163] op_sel_hi:[1,0]
	v_pk_mul_f32 v[124:125], v[124:125], v[160:161]
	v_pk_mul_f32 v[120:121], v[118:119], v[128:129]
	v_pk_mul_f32 v[118:119], v[116:117], v[130:131]
	v_pk_mul_f32 v[126:127], v[126:127], v[158:159]
	v_cvt_pk_bf16_f32 v116, v124, v125
	v_lshl_or_b32 v140, s0, 7, v146
	v_cvt_pk_bf16_f32 v117, v126, v127
	v_cvt_pk_bf16_f32 v118, v118, v119
	v_cvt_pk_bf16_f32 v119, v120, v121
	v_add_u32_e32 v152, s27, v144
	v_ashrrev_i32_e32 v141, 31, v140
	v_mov_b64_e32 v[142:143], s[16:17]
	v_mad_i64_i32 v[154:155], s[0:1], v152, s30, v[142:143]
	v_lshlrev_b64 v[140:141], 1, v[140:141]
	v_lshl_add_u64 v[154:155], v[154:155], 0, v[140:141]
	global_store_dwordx4 v[154:155], v[116:119], off
	v_pk_mul_f32 v[110:111], v[114:115], v[110:111]
	v_pk_mul_f32 v[108:109], v[112:113], v[108:109]
	v_mov_b32_e32 v124, v221
	v_mul_f32_e32 v118, 0xbfb8aa3b, v124
	v_pk_mul_f32 v[120:121], v[114:115], v[118:119] op_sel_hi:[1,0]
	v_pk_mul_f32 v[122:123], v[112:113], v[118:119] op_sel_hi:[1,0]
	v_pk_mul_f32 v[112:113], v[106:107], v[118:119] op_sel_hi:[1,0]
	v_pk_mul_f32 v[114:115], v[104:105], v[118:119] op_sel_hi:[1,0]
	v_exp_f32_e32 v122, v122
	v_exp_f32_e32 v123, v123
	v_exp_f32_e32 v114, v114
	v_exp_f32_e32 v112, v112
	v_exp_f32_e32 v113, v113
	v_exp_f32_e32 v115, v115
	v_exp_f32_e32 v120, v120
	v_exp_f32_e32 v121, v121
	v_pk_add_f32 v[122:123], v[122:123], 1.0 op_sel_hi:[1,0]
	v_pk_add_f32 v[112:113], v[112:113], 1.0 op_sel_hi:[1,0]
	v_pk_add_f32 v[114:115], v[114:115], 1.0 op_sel_hi:[1,0]
	v_pk_add_f32 v[120:121], v[120:121], 1.0 op_sel_hi:[1,0]
	v_rcp_f32_e32 v122, v122
	v_rcp_f32_e32 v123, v123
	v_rcp_f32_e32 v114, v114
	v_rcp_f32_e32 v115, v115
	v_rcp_f32_e32 v112, v112
	v_rcp_f32_e32 v113, v113
	v_rcp_f32_e32 v120, v120
	v_rcp_f32_e32 v121, v121
	v_mul_f32_e32 v124, v124, v124
	v_pk_mul_f32 v[102:103], v[106:107], v[102:103]
	v_pk_mul_f32 v[100:101], v[104:105], v[100:101]
	v_pk_mul_f32 v[108:109], v[108:109], v[124:125] op_sel_hi:[1,0]
	v_pk_mul_f32 v[100:101], v[100:101], v[124:125] op_sel_hi:[1,0]
	v_pk_mul_f32 v[102:103], v[102:103], v[124:125] op_sel_hi:[1,0]
	v_pk_mul_f32 v[110:111], v[110:111], v[124:125] op_sel_hi:[1,0]
	v_pk_mul_f32 v[108:109], v[108:109], v[122:123]
	v_pk_mul_f32 v[104:105], v[102:103], v[112:113]
	v_pk_mul_f32 v[102:103], v[100:101], v[114:115]
	v_pk_mul_f32 v[110:111], v[110:111], v[120:121]
	v_cvt_pk_bf16_f32 v100, v108, v109
	v_or_b32_e32 v116, 16, v152
	v_cvt_pk_bf16_f32 v101, v110, v111
	v_cvt_pk_bf16_f32 v102, v102, v103
	v_cvt_pk_bf16_f32 v103, v104, v105
	v_mad_i64_i32 v[116:117], s[0:1], v116, s30, v[142:143]
	v_lshl_add_u64 v[116:117], v[116:117], 0, v[140:141]
	global_store_dwordx4 v[116:117], v[100:103], off
	v_pk_mul_f32 v[90:91], v[94:95], v[90:91]
	v_pk_mul_f32 v[88:89], v[92:93], v[88:89]
	v_mov_b32_e32 v108, v222
	v_mul_f32_e32 v102, 0xbfb8aa3b, v108
	v_pk_mul_f32 v[104:105], v[94:95], v[102:103] op_sel_hi:[1,0]
	v_pk_mul_f32 v[106:107], v[92:93], v[102:103] op_sel_hi:[1,0]
	v_pk_mul_f32 v[92:93], v[86:87], v[102:103] op_sel_hi:[1,0]
	v_pk_mul_f32 v[94:95], v[84:85], v[102:103] op_sel_hi:[1,0]
	v_exp_f32_e32 v106, v106
	v_exp_f32_e32 v107, v107
	v_exp_f32_e32 v94, v94
	v_exp_f32_e32 v92, v92
	v_exp_f32_e32 v93, v93
	v_exp_f32_e32 v95, v95
	v_exp_f32_e32 v104, v104
	v_exp_f32_e32 v105, v105
	v_pk_add_f32 v[106:107], v[106:107], 1.0 op_sel_hi:[1,0]
	v_pk_add_f32 v[92:93], v[92:93], 1.0 op_sel_hi:[1,0]
	v_pk_add_f32 v[94:95], v[94:95], 1.0 op_sel_hi:[1,0]
	v_pk_add_f32 v[104:105], v[104:105], 1.0 op_sel_hi:[1,0]
	v_rcp_f32_e32 v106, v106
	v_rcp_f32_e32 v107, v107
	v_rcp_f32_e32 v94, v94
	v_rcp_f32_e32 v95, v95
	v_rcp_f32_e32 v92, v92
	v_rcp_f32_e32 v93, v93
	v_rcp_f32_e32 v104, v104
	v_rcp_f32_e32 v105, v105
	v_mul_f32_e32 v108, v108, v108
	v_pk_mul_f32 v[82:83], v[86:87], v[82:83]
	v_pk_mul_f32 v[80:81], v[84:85], v[80:81]
	v_pk_mul_f32 v[88:89], v[88:89], v[108:109] op_sel_hi:[1,0]
	v_pk_mul_f32 v[80:81], v[80:81], v[108:109] op_sel_hi:[1,0]
	v_pk_mul_f32 v[82:83], v[82:83], v[108:109] op_sel_hi:[1,0]
	v_pk_mul_f32 v[90:91], v[90:91], v[108:109] op_sel_hi:[1,0]
	v_pk_mul_f32 v[88:89], v[88:89], v[106:107]
	v_pk_mul_f32 v[84:85], v[82:83], v[92:93]
	v_pk_mul_f32 v[82:83], v[80:81], v[94:95]
	v_pk_mul_f32 v[90:91], v[90:91], v[104:105]
	v_cvt_pk_bf16_f32 v80, v88, v89
	v_or_b32_e32 v100, 32, v152
	v_cvt_pk_bf16_f32 v81, v90, v91
	v_cvt_pk_bf16_f32 v82, v82, v83
	v_cvt_pk_bf16_f32 v83, v84, v85
	v_mad_i64_i32 v[100:101], s[0:1], v100, s30, v[142:143]
	v_lshl_add_u64 v[100:101], v[100:101], 0, v[140:141]
	global_store_dwordx4 v[100:101], v[80:83], off
	v_pk_mul_f32 v[74:75], v[78:79], v[74:75]
	v_pk_mul_f32 v[72:73], v[76:77], v[72:73]
	v_mov_b32_e32 v88, v223
	v_mul_f32_e32 v82, 0xbfb8aa3b, v88
	v_pk_mul_f32 v[84:85], v[78:79], v[82:83] op_sel_hi:[1,0]
	v_pk_mul_f32 v[86:87], v[76:77], v[82:83] op_sel_hi:[1,0]
	v_pk_mul_f32 v[76:77], v[70:71], v[82:83] op_sel_hi:[1,0]
	v_pk_mul_f32 v[78:79], v[68:69], v[82:83] op_sel_hi:[1,0]
	v_exp_f32_e32 v86, v86
	v_exp_f32_e32 v87, v87
	v_exp_f32_e32 v78, v78
	v_exp_f32_e32 v76, v76
	v_exp_f32_e32 v77, v77
	v_exp_f32_e32 v79, v79
	v_exp_f32_e32 v84, v84
	v_exp_f32_e32 v85, v85
	v_pk_add_f32 v[86:87], v[86:87], 1.0 op_sel_hi:[1,0]
	v_pk_add_f32 v[76:77], v[76:77], 1.0 op_sel_hi:[1,0]
	v_pk_add_f32 v[78:79], v[78:79], 1.0 op_sel_hi:[1,0]
	v_pk_add_f32 v[84:85], v[84:85], 1.0 op_sel_hi:[1,0]
	v_rcp_f32_e32 v86, v86
	v_rcp_f32_e32 v87, v87
	v_rcp_f32_e32 v78, v78
	v_rcp_f32_e32 v79, v79
	v_rcp_f32_e32 v76, v76
	v_rcp_f32_e32 v77, v77
	v_rcp_f32_e32 v84, v84
	v_rcp_f32_e32 v85, v85
	v_mul_f32_e32 v88, v88, v88
	v_pk_mul_f32 v[66:67], v[70:71], v[66:67]
	v_pk_mul_f32 v[64:65], v[68:69], v[64:65]
	v_pk_mul_f32 v[72:73], v[72:73], v[88:89] op_sel_hi:[1,0]
	v_pk_mul_f32 v[64:65], v[64:65], v[88:89] op_sel_hi:[1,0]
	v_pk_mul_f32 v[66:67], v[66:67], v[88:89] op_sel_hi:[1,0]
	v_pk_mul_f32 v[74:75], v[74:75], v[88:89] op_sel_hi:[1,0]
	v_pk_mul_f32 v[72:73], v[72:73], v[86:87]
	v_pk_mul_f32 v[68:69], v[66:67], v[76:77]
	v_pk_mul_f32 v[66:67], v[64:65], v[78:79]
	v_pk_mul_f32 v[74:75], v[74:75], v[84:85]
	v_cvt_pk_bf16_f32 v64, v72, v73
	v_or_b32_e32 v80, 48, v152
	v_cvt_pk_bf16_f32 v65, v74, v75
	v_cvt_pk_bf16_f32 v66, v66, v67
	v_cvt_pk_bf16_f32 v67, v68, v69
	v_mad_i64_i32 v[80:81], s[0:1], v80, s30, v[142:143]
	v_lshl_add_u64 v[80:81], v[80:81], 0, v[140:141]
	global_store_dwordx4 v[80:81], v[64:67], off
	v_pk_mul_f32 v[58:59], v[62:63], v[58:59]
	v_pk_mul_f32 v[56:57], v[60:61], v[56:57]
	v_mov_b32_e32 v72, v224
	v_mul_f32_e32 v66, 0xbfb8aa3b, v72
	v_pk_mul_f32 v[68:69], v[62:63], v[66:67] op_sel_hi:[1,0]
	v_pk_mul_f32 v[70:71], v[60:61], v[66:67] op_sel_hi:[1,0]
	v_pk_mul_f32 v[60:61], v[54:55], v[66:67] op_sel_hi:[1,0]
	v_pk_mul_f32 v[62:63], v[52:53], v[66:67] op_sel_hi:[1,0]
	v_exp_f32_e32 v70, v70
	v_exp_f32_e32 v71, v71
	v_exp_f32_e32 v62, v62
	v_exp_f32_e32 v60, v60
	v_exp_f32_e32 v61, v61
	v_exp_f32_e32 v63, v63
	v_exp_f32_e32 v68, v68
	v_exp_f32_e32 v69, v69
	v_pk_add_f32 v[70:71], v[70:71], 1.0 op_sel_hi:[1,0]
	v_pk_add_f32 v[60:61], v[60:61], 1.0 op_sel_hi:[1,0]
	v_pk_add_f32 v[62:63], v[62:63], 1.0 op_sel_hi:[1,0]
	v_pk_add_f32 v[68:69], v[68:69], 1.0 op_sel_hi:[1,0]
	v_rcp_f32_e32 v70, v70
	v_rcp_f32_e32 v71, v71
	v_rcp_f32_e32 v62, v62
	v_rcp_f32_e32 v63, v63
	v_rcp_f32_e32 v60, v60
	v_rcp_f32_e32 v61, v61
	v_rcp_f32_e32 v68, v68
	v_rcp_f32_e32 v69, v69
	v_mul_f32_e32 v72, v72, v72
	v_pk_mul_f32 v[50:51], v[54:55], v[50:51]
	v_pk_mul_f32 v[48:49], v[52:53], v[48:49]
	v_pk_mul_f32 v[56:57], v[56:57], v[72:73] op_sel_hi:[1,0]
	v_pk_mul_f32 v[48:49], v[48:49], v[72:73] op_sel_hi:[1,0]
	v_pk_mul_f32 v[50:51], v[50:51], v[72:73] op_sel_hi:[1,0]
	v_pk_mul_f32 v[58:59], v[58:59], v[72:73] op_sel_hi:[1,0]
	v_pk_mul_f32 v[56:57], v[56:57], v[70:71]
	v_pk_mul_f32 v[52:53], v[50:51], v[60:61]
	v_pk_mul_f32 v[50:51], v[48:49], v[62:63]
	v_pk_mul_f32 v[58:59], v[58:59], v[68:69]
	v_cvt_pk_bf16_f32 v48, v56, v57
	v_add_u32_e32 v64, 0x80, v152
	v_cvt_pk_bf16_f32 v49, v58, v59
	v_cvt_pk_bf16_f32 v50, v50, v51
	v_cvt_pk_bf16_f32 v51, v52, v53
	v_mad_i64_i32 v[64:65], s[0:1], v64, s30, v[142:143]
	v_lshl_add_u64 v[64:65], v[64:65], 0, v[140:141]
	global_store_dwordx4 v[64:65], v[48:51], off
	v_pk_mul_f32 v[42:43], v[46:47], v[42:43]
	v_pk_mul_f32 v[40:41], v[44:45], v[40:41]
	v_mov_b32_e32 v56, v225
	v_mul_f32_e32 v50, 0xbfb8aa3b, v56
	v_pk_mul_f32 v[52:53], v[46:47], v[50:51] op_sel_hi:[1,0]
	v_pk_mul_f32 v[54:55], v[44:45], v[50:51] op_sel_hi:[1,0]
	v_pk_mul_f32 v[44:45], v[38:39], v[50:51] op_sel_hi:[1,0]
	v_pk_mul_f32 v[46:47], v[36:37], v[50:51] op_sel_hi:[1,0]
	v_exp_f32_e32 v54, v54
	v_exp_f32_e32 v55, v55
	v_exp_f32_e32 v46, v46
	v_exp_f32_e32 v44, v44
	v_exp_f32_e32 v45, v45
	v_exp_f32_e32 v47, v47
	v_exp_f32_e32 v52, v52
	v_exp_f32_e32 v53, v53
	v_pk_add_f32 v[54:55], v[54:55], 1.0 op_sel_hi:[1,0]
	v_pk_add_f32 v[44:45], v[44:45], 1.0 op_sel_hi:[1,0]
	v_pk_add_f32 v[46:47], v[46:47], 1.0 op_sel_hi:[1,0]
	v_pk_add_f32 v[52:53], v[52:53], 1.0 op_sel_hi:[1,0]
	v_rcp_f32_e32 v54, v54
	v_rcp_f32_e32 v55, v55
	v_rcp_f32_e32 v46, v46
	v_rcp_f32_e32 v47, v47
	v_rcp_f32_e32 v44, v44
	v_rcp_f32_e32 v45, v45
	v_rcp_f32_e32 v52, v52
	v_rcp_f32_e32 v53, v53
	v_mul_f32_e32 v56, v56, v56
	v_pk_mul_f32 v[34:35], v[38:39], v[34:35]
	v_pk_mul_f32 v[32:33], v[36:37], v[32:33]
	v_pk_mul_f32 v[40:41], v[40:41], v[56:57] op_sel_hi:[1,0]
	v_pk_mul_f32 v[32:33], v[32:33], v[56:57] op_sel_hi:[1,0]
	v_pk_mul_f32 v[34:35], v[34:35], v[56:57] op_sel_hi:[1,0]
	v_pk_mul_f32 v[42:43], v[42:43], v[56:57] op_sel_hi:[1,0]
	v_pk_mul_f32 v[40:41], v[40:41], v[54:55]
	v_pk_mul_f32 v[36:37], v[34:35], v[44:45]
	v_pk_mul_f32 v[34:35], v[32:33], v[46:47]
	v_pk_mul_f32 v[42:43], v[42:43], v[52:53]
	v_cvt_pk_bf16_f32 v32, v40, v41
	v_add_u32_e32 v48, 0x90, v152
	v_cvt_pk_bf16_f32 v33, v42, v43
	v_cvt_pk_bf16_f32 v34, v34, v35
	v_cvt_pk_bf16_f32 v35, v36, v37
	v_mad_i64_i32 v[48:49], s[0:1], v48, s30, v[142:143]
	v_lshl_add_u64 v[48:49], v[48:49], 0, v[140:141]
	global_store_dwordx4 v[48:49], v[32:35], off
	v_pk_mul_f32 v[26:27], v[30:31], v[26:27]
	v_pk_mul_f32 v[24:25], v[28:29], v[24:25]
	v_mov_b32_e32 v40, v226
	v_mul_f32_e32 v34, 0xbfb8aa3b, v40
	v_pk_mul_f32 v[36:37], v[30:31], v[34:35] op_sel_hi:[1,0]
	v_pk_mul_f32 v[38:39], v[28:29], v[34:35] op_sel_hi:[1,0]
	v_pk_mul_f32 v[28:29], v[22:23], v[34:35] op_sel_hi:[1,0]
	v_pk_mul_f32 v[30:31], v[20:21], v[34:35] op_sel_hi:[1,0]
	v_exp_f32_e32 v38, v38
	v_exp_f32_e32 v39, v39
	v_exp_f32_e32 v30, v30
	v_exp_f32_e32 v28, v28
	v_exp_f32_e32 v29, v29
	v_exp_f32_e32 v31, v31
	v_exp_f32_e32 v36, v36
	v_exp_f32_e32 v37, v37
	v_pk_add_f32 v[38:39], v[38:39], 1.0 op_sel_hi:[1,0]
	v_pk_add_f32 v[28:29], v[28:29], 1.0 op_sel_hi:[1,0]
	v_pk_add_f32 v[30:31], v[30:31], 1.0 op_sel_hi:[1,0]
	v_pk_add_f32 v[36:37], v[36:37], 1.0 op_sel_hi:[1,0]
	v_rcp_f32_e32 v38, v38
	v_rcp_f32_e32 v39, v39
	v_rcp_f32_e32 v30, v30
	v_rcp_f32_e32 v31, v31
	v_rcp_f32_e32 v28, v28
	v_rcp_f32_e32 v29, v29
	v_rcp_f32_e32 v36, v36
	v_rcp_f32_e32 v37, v37
	v_mul_f32_e32 v40, v40, v40
	v_pk_mul_f32 v[18:19], v[22:23], v[18:19]
	v_pk_mul_f32 v[16:17], v[20:21], v[16:17]
	v_pk_mul_f32 v[24:25], v[24:25], v[40:41] op_sel_hi:[1,0]
	v_pk_mul_f32 v[16:17], v[16:17], v[40:41] op_sel_hi:[1,0]
	v_pk_mul_f32 v[18:19], v[18:19], v[40:41] op_sel_hi:[1,0]
	v_pk_mul_f32 v[26:27], v[26:27], v[40:41] op_sel_hi:[1,0]
	v_pk_mul_f32 v[24:25], v[24:25], v[38:39]
	v_pk_mul_f32 v[20:21], v[18:19], v[28:29]
	v_pk_mul_f32 v[18:19], v[16:17], v[30:31]
	v_pk_mul_f32 v[26:27], v[26:27], v[36:37]
	v_cvt_pk_bf16_f32 v16, v24, v25
	v_add_u32_e32 v32, 0xa0, v152
	v_cvt_pk_bf16_f32 v17, v26, v27
	v_cvt_pk_bf16_f32 v18, v18, v19
	v_cvt_pk_bf16_f32 v19, v20, v21
	v_mad_i64_i32 v[32:33], s[0:1], v32, s30, v[142:143]
	v_lshl_add_u64 v[32:33], v[32:33], 0, v[140:141]
	global_store_dwordx4 v[32:33], v[16:19], off
	v_pk_mul_f32 v[10:11], v[14:15], v[10:11]
	v_pk_mul_f32 v[8:9], v[12:13], v[8:9]
	v_mov_b32_e32 v24, v227
	v_mul_f32_e32 v18, 0xbfb8aa3b, v24
	v_pk_mul_f32 v[20:21], v[14:15], v[18:19] op_sel_hi:[1,0]
	v_pk_mul_f32 v[22:23], v[12:13], v[18:19] op_sel_hi:[1,0]
	v_pk_mul_f32 v[12:13], v[6:7], v[18:19] op_sel_hi:[1,0]
	v_pk_mul_f32 v[14:15], v[4:5], v[18:19] op_sel_hi:[1,0]
	v_exp_f32_e32 v12, v12
	v_exp_f32_e32 v14, v14
	v_exp_f32_e32 v13, v13
	v_exp_f32_e32 v15, v15
	v_exp_f32_e32 v22, v22
	v_exp_f32_e32 v20, v20
	v_exp_f32_e32 v21, v21
	v_exp_f32_e32 v23, v23
	v_pk_add_f32 v[12:13], v[12:13], 1.0 op_sel_hi:[1,0]
	v_pk_add_f32 v[14:15], v[14:15], 1.0 op_sel_hi:[1,0]
	v_pk_add_f32 v[20:21], v[20:21], 1.0 op_sel_hi:[1,0]
	v_pk_add_f32 v[22:23], v[22:23], 1.0 op_sel_hi:[1,0]
	v_rcp_f32_e32 v14, v14
	v_rcp_f32_e32 v15, v15
	v_rcp_f32_e32 v12, v12
	v_rcp_f32_e32 v13, v13
	v_rcp_f32_e32 v22, v22
	v_rcp_f32_e32 v23, v23
	v_rcp_f32_e32 v20, v20
	v_rcp_f32_e32 v21, v21
	v_add_u32_e32 v16, 0xb0, v152
	v_mul_f32_e32 v24, v24, v24
	v_pk_mul_f32 v[2:3], v[6:7], v[2:3]
	v_pk_mul_f32 v[0:1], v[4:5], v[0:1]
	v_mad_i64_i32 v[16:17], s[0:1], v16, s30, v[142:143]
	v_pk_mul_f32 v[0:1], v[0:1], v[24:25] op_sel_hi:[1,0]
	v_pk_mul_f32 v[2:3], v[2:3], v[24:25] op_sel_hi:[1,0]
	v_lshl_add_u64 v[16:17], v[16:17], 0, v[140:141]
	v_pk_mul_f32 v[8:9], v[8:9], v[24:25] op_sel_hi:[1,0]
	v_pk_mul_f32 v[10:11], v[10:11], v[24:25] op_sel_hi:[1,0]
	v_pk_mul_f32 v[4:5], v[2:3], v[12:13]
	v_pk_mul_f32 v[2:3], v[0:1], v[14:15]
	s_andn2_b64 vcc, exec, s[72:73]
	s_mov_b64 s[72:73], -1
	v_pk_mul_f32 v[10:11], v[10:11], v[20:21]
	v_pk_mul_f32 v[8:9], v[8:9], v[22:23]
	s_nop 0
	v_cvt_pk_bf16_f32 v0, v8, v9
	v_cvt_pk_bf16_f32 v1, v10, v11
	v_cvt_pk_bf16_f32 v2, v2, v3
	v_cvt_pk_bf16_f32 v3, v4, v5
	global_store_dwordx4 v[16:17], v[0:3], off
	s_cbranch_vccnz .LBB0_341
	s_andn2_b64 vcc, exec, s[8:9]
	s_cbranch_vccnz .LBB0_340
	s_barrier
	s_branch .LBB0_340
